# norm_static ctx rows (ph4, ph7): all 16 row loads issued up front with one wait, DPP+permlane row sum instead of 6 ds_bpermute, drain waits removed
# baseline (speedup 1.0000x reference)
; DI int tidx() { int t = threadIdx.x; asm volatile("" : "+v"(t)); return t; }
; DI void norm_row(const Params& p, int layer, int which, int t, int lane) {
;   const float* g = (which ? p.norm_ffn : p.norm_attn) + layer * DM;
;   const float* xr = which ? (const float*)xrow_dst(p, t) : xrow_src(p, layer, t);
;   const float* md = p.mod + ((size_t)layer * 5 + mb_of(t)) * 6144 + (which ? 3 * 1024 : 0);
;   float4 v[4];
;   float ss = 0.f;
; #pragma unroll
;   for (int j = 0; j < 4; ++j) {
;     v[j] = *(const float4*)(xr + lane * 4 + 256 * j);
;     ss += v[j].x * v[j].x + v[j].y * v[j].y + v[j].z * v[j].z + v[j].w * v[j].w;
;   }
; #pragma unroll
;   for (int o = 32; o >= 1; o >>= 1) ss += __shfl_xor(ss, o);
;   float r = rsqrtf(ss * (1.f / 1024.f) + EPSV);
; #pragma unroll
;   for (int j = 0; j < 4; ++j) {
;     int col = lane * 4 + 256 * j;
;     float4 gg = *(const float4*)(g + col);
;     float4 sh = *(const float4*)(md + col);
;     float4 sc = *(const float4*)(md + 1024 + col);
;     float o0 = v[j].x * r * gg.x * (1.f + sc.x) + sh.x;
;     float o1 = v[j].y * r * gg.y * (1.f + sc.y) + sh.y;
;     float o2 = v[j].z * r * gg.z * (1.f + sc.z) + sh.z;
;     float o3 = v[j].w * r * gg.w * (1.f + sc.w) + sh.w;
;     *(uint2*)(p.H + (size_t)t * LDK + col) = make_uint2(pack_bf16(o0, o1), pack_bf16(o2, o3));
;   }
; }
; DI void norm_static(const Params& p, int layer, int which, int row0, int row1) {
;   const int tid = tidx(), lane = tid & 63, wid = tid >> 6;
;   for (int t = row0 + blockIdx.x * 8 + wid; t < row1; t += gridDim.x * 8) norm_row(p, layer, which, t, lane);
.LBB0_143:
	v_add_u32_e32 v2, 0x4000, v50
	v_mov_b64_e32 v[4:5], s[36:37]
	v_mov_b64_e32 v[6:7], s[76:77]
	v_mov_b64_e32 v[8:9], s[40:41]
	v_mov_b64_e32 v[10:11], s[64:65]
	v_cmp_gt_i32_e32 vcc, s13, v2
	v_ashrrev_i32_e32 v3, 31, v2
	v_cndmask_b32_e64 v8, v10, v8, s[4:5]
	v_cndmask_b32_e64 v9, v11, v9, s[4:5]
	v_cndmask_b32_e64 v6, v6, v4, s[4:5]
	v_cndmask_b32_e64 v7, v7, v5, s[4:5]
	v_cndmask_b32_e32 v5, 0, v3, vcc
	v_cndmask_b32_e32 v4, v50, v2, vcc
	v_cndmask_b32_e32 v7, v9, v7, vcc
	v_cndmask_b32_e32 v6, v8, v6, vcc
	v_lshlrev_b64 v[4:5], 12, v[4:5]
	v_lshl_add_u64 v[4:5], v[6:7], 0, v[4:5]
	v_lshl_add_u64 v[14:15], v[4:5], 0, v[0:1]
	v_and_b32_e32 v4, 64, v211
	v_add_u32_e32 v4, 64, v4
	v_xor_b32_e32 v5, 32, v211
	v_cmp_lt_i32_e32 vcc, v5, v4
	v_min_i32_e32 v6, 0x4000, v2
	v_ashrrev_i32_e32 v6, 12, v6
	v_cndmask_b32_e32 v5, v211, v5, vcc
	v_lshlrev_b32_e32 v51, 2, v5
	v_xor_b32_e32 v5, 16, v211
	v_cmp_lt_i32_e32 vcc, v5, v4
	v_add_u32_e32 v6, s12, v6
	v_mul_hi_i32_i24_e32 v7, 0x6000, v6
	v_cndmask_b32_e32 v5, v211, v5, vcc
	v_lshlrev_b32_e32 v52, 2, v5
	v_xor_b32_e32 v5, 8, v211
	v_cmp_lt_i32_e32 vcc, v5, v4
	v_mul_i32_i24_e32 v6, 0x6000, v6
	v_lshl_add_u64 v[6:7], s[62:63], 0, v[6:7]
	v_cndmask_b32_e32 v5, v211, v5, vcc
	v_lshlrev_b32_e32 v53, 2, v5
	v_xor_b32_e32 v5, 4, v211
	v_cmp_lt_i32_e32 vcc, v5, v4
	v_lshl_add_u64 v[16:17], v[6:7], 0, s[18:19]
	v_lshl_add_u64 v[18:19], v[16:17], 0, v[0:1]
	v_cndmask_b32_e32 v5, v211, v5, vcc
	v_lshlrev_b32_e32 v64, 2, v5
	v_xor_b32_e32 v5, 2, v211
	v_cmp_lt_i32_e32 vcc, v5, v4
	v_lshlrev_b64 v[22:23], 11, v[2:3]
	v_lshl_add_u64 v[38:39], v[6:7], 0, v[0:1]
	v_cndmask_b32_e32 v5, v211, v5, vcc
	v_lshlrev_b32_e32 v65, 2, v5
	v_xor_b32_e32 v5, 1, v211
	v_cmp_lt_i32_e32 vcc, v5, v4
	v_lshl_add_u64 v[36:37], v[28:29], 0, v[22:23]
	v_mov_b32_e32 v31, v1
	v_cndmask_b32_e32 v4, v211, v5, vcc
	v_lshlrev_b32_e32 v66, 2, v4
	global_load_dwordx4 v[158:161], v[14:15], off
	global_load_dwordx4 v[162:165], v[14:15], off offset:1024
	global_load_dwordx4 v[166:169], v[14:15], off offset:2048
	global_load_dwordx4 v[170:173], v[14:15], off offset:3072
	global_load_dwordx4 v[174:177], v[26:27], off
	global_load_dwordx4 v[202:205], v[38:39], off
	global_load_dwordx4 v[10:13], v[18:19], off
	global_load_dwordx4 v[186:189], v[26:27], off offset:1024
	global_load_dwordx4 v[206:209], v[38:39], off offset:1024
	global_load_dwordx4 v[20:23], v[18:19], off offset:1024
	global_load_dwordx4 v[190:193], v[26:27], off offset:2048
	global_load_dwordx4 v[2:5], v[38:39], off offset:2048
	global_load_dwordx4 v[30:33], v[18:19], off offset:2048
	global_load_dwordx4 v[198:201], v[26:27], off offset:3072
	global_load_dwordx4 v[6:9], v[38:39], off offset:3072
	global_load_dwordx4 v[40:43], v[18:19], off offset:3072
	v_add_u32_e32 v50, s14, v50
	s_waitcnt vmcnt(12)
	v_mul_f32_e32 v56, v158, v158
	v_mul_f32_e32 v57, v159, v159
	v_fmac_f32_e32 v56, v160, v160
	v_fmac_f32_e32 v57, v161, v161
	v_fmac_f32_e32 v56, v162, v162
	v_fmac_f32_e32 v57, v163, v163
	v_fmac_f32_e32 v56, v164, v164
	v_fmac_f32_e32 v57, v165, v165
	v_fmac_f32_e32 v56, v166, v166
	v_fmac_f32_e32 v57, v167, v167
	v_fmac_f32_e32 v56, v168, v168
	v_fmac_f32_e32 v57, v169, v169
	v_fmac_f32_e32 v56, v170, v170
	v_fmac_f32_e32 v57, v171, v171
	v_fmac_f32_e32 v56, v172, v172
	v_fmac_f32_e32 v57, v173, v173
	v_add_f32_e32 v56, v56, v57
	s_nop 1
	v_add_f32_dpp v56, v56, v56 quad_perm:[1,0,3,2] row_mask:0xf bank_mask:0xf
	s_nop 1
	v_add_f32_dpp v56, v56, v56 quad_perm:[2,3,0,1] row_mask:0xf bank_mask:0xf
	s_nop 1
	v_add_f32_dpp v56, v56, v56 row_half_mirror row_mask:0xf bank_mask:0xf
	s_nop 1
	v_add_f32_dpp v56, v56, v56 row_mirror row_mask:0xf bank_mask:0xf
	v_mov_b32_e32 v57, v56
	s_nop 1
	v_permlane16_swap_b32_e32 v56, v57
	v_add_f32_e32 v56, v56, v57
	v_mov_b32_e32 v57, v56
	s_nop 1
	v_permlane32_swap_b32_e32 v56, v57
	v_add_f32_e32 v56, v56, v57
	v_fmamk_f32 v56, v56, 0x3a800000, v210
	v_cmp_gt_f32_e32 vcc, s15, v56
	v_mul_f32_e32 v57, 0x4b800000, v56
	s_nop 0
	v_cndmask_b32_e32 v56, v56, v57, vcc
	v_rsq_f32_e32 v56, v56
	s_nop 0
	v_mul_f32_e32 v57, 0x45800000, v56
	v_cndmask_b32_e32 v58, v56, v57, vcc
	s_waitcnt vmcnt(0)
	v_mul_f32_e32 v158, v158, v58
	v_add_f32_e32 v10, 1.0, v10
	v_mul_f32_e32 v158, v174, v158
	v_fma_f32 v158, v158, v10, v202
	v_mul_f32_e32 v159, v159, v58
	v_add_f32_e32 v11, 1.0, v11
	v_mul_f32_e32 v159, v175, v159
	v_fma_f32 v159, v159, v11, v203
	v_mul_f32_e32 v160, v160, v58
	v_add_f32_e32 v12, 1.0, v12
	v_mul_f32_e32 v160, v176, v160
	v_fma_f32 v160, v160, v12, v204
	v_mul_f32_e32 v161, v161, v58
	v_add_f32_e32 v13, 1.0, v13
	v_mul_f32_e32 v161, v177, v161
	v_fma_f32 v161, v161, v13, v205
	v_cvt_pk_bf16_f32 v158, v158, v159
	v_cvt_pk_bf16_f32 v159, v160, v161
	global_store_dwordx2 v[36:37], v[158:159], off
	v_mul_f32_e32 v162, v162, v58
	v_add_f32_e32 v20, 1.0, v20
	v_mul_f32_e32 v162, v186, v162
	v_fma_f32 v162, v162, v20, v206
	v_mul_f32_e32 v163, v163, v58
	v_add_f32_e32 v21, 1.0, v21
	v_mul_f32_e32 v163, v187, v163
	v_fma_f32 v163, v163, v21, v207
	v_mul_f32_e32 v164, v164, v58
	v_add_f32_e32 v22, 1.0, v22
	v_mul_f32_e32 v164, v188, v164
	v_fma_f32 v164, v164, v22, v208
	v_mul_f32_e32 v165, v165, v58
	v_add_f32_e32 v23, 1.0, v23
	v_mul_f32_e32 v165, v189, v165
	v_fma_f32 v165, v165, v23, v209
	v_cvt_pk_bf16_f32 v162, v162, v163
	v_cvt_pk_bf16_f32 v163, v164, v165
	global_store_dwordx2 v[36:37], v[162:163], off offset:512
	v_mul_f32_e32 v166, v166, v58
	v_add_f32_e32 v30, 1.0, v30
	v_mul_f32_e32 v166, v190, v166
	v_fma_f32 v166, v166, v30, v2
	v_mul_f32_e32 v167, v167, v58
	v_add_f32_e32 v31, 1.0, v31
	v_mul_f32_e32 v167, v191, v167
	v_fma_f32 v167, v167, v31, v3
	v_mul_f32_e32 v168, v168, v58
	v_add_f32_e32 v32, 1.0, v32
	v_mul_f32_e32 v168, v192, v168
	v_fma_f32 v168, v168, v32, v4
	v_mul_f32_e32 v169, v169, v58
	v_add_f32_e32 v33, 1.0, v33
	v_mul_f32_e32 v169, v193, v169
	v_fma_f32 v169, v169, v33, v5
	v_cvt_pk_bf16_f32 v166, v166, v167
	v_cvt_pk_bf16_f32 v167, v168, v169
	global_store_dwordx2 v[36:37], v[166:167], off offset:1024
	v_mul_f32_e32 v170, v170, v58
	v_add_f32_e32 v40, 1.0, v40
	v_mul_f32_e32 v170, v198, v170
	v_fma_f32 v170, v170, v40, v6
	v_mul_f32_e32 v171, v171, v58
	v_add_f32_e32 v41, 1.0, v41
	v_mul_f32_e32 v171, v199, v171
	v_fma_f32 v171, v171, v41, v7
	v_mul_f32_e32 v172, v172, v58
	v_add_f32_e32 v42, 1.0, v42
	v_mul_f32_e32 v172, v200, v172
	v_fma_f32 v172, v172, v42, v8
	v_mul_f32_e32 v173, v173, v58
	v_add_f32_e32 v43, 1.0, v43
	v_mul_f32_e32 v173, v201, v173
	v_fma_f32 v173, v173, v43, v9
	v_cvt_pk_bf16_f32 v170, v170, v171
	v_cvt_pk_bf16_f32 v171, v172, v173
	global_store_dwordx2 v[36:37], v[170:171], off offset:1536
	v_add_u32_e32 v2, 0x4000, v50
	v_cmp_lt_i32_e32 vcc, s16, v2
	s_or_b64 s[2:3], vcc, s[2:3]
	s_andn2_b64 exec, exec, s[2:3]
	s_cbranch_execnz .LBB0_143

; DI int tidx() { int t = threadIdx.x; asm volatile("" : "+v"(t)); return t; }
; DI void norm_row(const Params& p, int layer, int which, int t, int lane) {
;   const float* g = (which ? p.norm_ffn : p.norm_attn) + layer * DM;
;   const float* xr = which ? (const float*)xrow_dst(p, t) : xrow_src(p, layer, t);
;   const float* md = p.mod + ((size_t)layer * 5 + mb_of(t)) * 6144 + (which ? 3 * 1024 : 0);
;   float4 v[4];
;   float ss = 0.f;
; #pragma unroll
;   for (int j = 0; j < 4; ++j) {
;     v[j] = *(const float4*)(xr + lane * 4 + 256 * j);
;     ss += v[j].x * v[j].x + v[j].y * v[j].y + v[j].z * v[j].z + v[j].w * v[j].w;
;   }
; #pragma unroll
;   for (int o = 32; o >= 1; o >>= 1) ss += __shfl_xor(ss, o);
;   float r = rsqrtf(ss * (1.f / 1024.f) + EPSV);
; #pragma unroll
;   for (int j = 0; j < 4; ++j) {
;     int col = lane * 4 + 256 * j;
;     float4 gg = *(const float4*)(g + col);
;     float4 sh = *(const float4*)(md + col);
;     float4 sc = *(const float4*)(md + 1024 + col);
;     float o0 = v[j].x * r * gg.x * (1.f + sc.x) + sh.x;
;     float o1 = v[j].y * r * gg.y * (1.f + sc.y) + sh.y;
;     float o2 = v[j].z * r * gg.z * (1.f + sc.z) + sh.z;
;     float o3 = v[j].w * r * gg.w * (1.f + sc.w) + sh.w;
;     *(uint2*)(p.H + (size_t)t * LDK + col) = make_uint2(pack_bf16(o0, o1), pack_bf16(o2, o3));
;   }
; }
; DI void norm_static(const Params& p, int layer, int which, int row0, int row1) {
;   const int tid = tidx(), lane = tid & 63, wid = tid >> 6;
;   for (int t = row0 + blockIdx.x * 8 + wid; t < row1; t += gridDim.x * 8) norm_row(p, layer, which, t, lane);
.LBB0_223:
	v_add_u32_e32 v2, 0x4000, v54
	v_mov_b64_e32 v[4:5], s[76:77]
	v_mov_b64_e32 v[6:7], s[64:65]
	v_cmp_gt_i32_e32 vcc, s10, v2
	v_ashrrev_i32_e32 v3, 31, v2
	v_lshlrev_b64 v[22:23], 11, v[2:3]
	v_cndmask_b32_e32 v9, 0, v3, vcc
	v_cndmask_b32_e32 v8, v54, v2, vcc
	v_cndmask_b32_e32 v5, v7, v5, vcc
	v_cndmask_b32_e32 v4, v6, v4, vcc
	v_lshlrev_b64 v[6:7], 12, v[8:9]
	v_lshl_add_u64 v[4:5], v[4:5], 0, v[6:7]
	v_lshl_add_u64 v[18:19], v[4:5], 0, v[0:1]
	v_and_b32_e32 v4, 64, v211
	v_add_u32_e32 v4, 64, v4
	v_xor_b32_e32 v5, 32, v211
	v_cmp_lt_i32_e32 vcc, v5, v4
	v_min_i32_e32 v6, 0x4000, v2
	v_ashrrev_i32_e32 v6, 12, v6
	v_cndmask_b32_e32 v5, v211, v5, vcc
	v_lshlrev_b32_e32 v55, 2, v5
	v_xor_b32_e32 v5, 16, v211
	v_cmp_lt_i32_e32 vcc, v5, v4
	v_add_u32_e32 v6, s8, v6
	v_mul_hi_i32_i24_e32 v7, 0x6000, v6
	v_cndmask_b32_e32 v5, v211, v5, vcc
	v_lshlrev_b32_e32 v56, 2, v5
	v_xor_b32_e32 v5, 8, v211
	v_cmp_lt_i32_e32 vcc, v5, v4
	v_mul_i32_i24_e32 v6, 0x6000, v6
	v_lshl_add_u64 v[6:7], s[62:63], 0, v[6:7]
	v_cndmask_b32_e32 v5, v211, v5, vcc
	v_lshlrev_b32_e32 v57, 2, v5
	v_xor_b32_e32 v5, 4, v211
	v_cmp_lt_i32_e32 vcc, v5, v4
	v_lshl_add_u64 v[20:21], v[6:7], 0, s[18:19]
	v_lshl_add_u64 v[46:47], v[6:7], 0, s[96:97]
	v_cndmask_b32_e32 v5, v211, v5, vcc
	v_lshlrev_b32_e32 v68, 2, v5
	v_xor_b32_e32 v5, 2, v211
	v_cmp_lt_i32_e32 vcc, v5, v4
	v_lshl_add_u64 v[2:3], v[20:21], 0, v[0:1]
	v_lshl_add_u64 v[14:15], v[46:47], 0, v[0:1]
	v_cndmask_b32_e32 v5, v211, v5, vcc
	v_lshlrev_b32_e32 v69, 2, v5
	v_xor_b32_e32 v5, 1, v211
	v_cmp_lt_i32_e32 vcc, v5, v4
	v_lshl_add_u64 v[36:37], v[28:29], 0, v[22:23]
	v_mov_b32_e32 v31, v1
	v_cndmask_b32_e32 v4, v211, v5, vcc
	v_lshlrev_b32_e32 v70, 2, v4
	global_load_dwordx4 v[148:151], v[18:19], off
	global_load_dwordx4 v[152:155], v[18:19], off offset:1024
	global_load_dwordx4 v[156:159], v[18:19], off offset:2048
	global_load_dwordx4 v[160:163], v[18:19], off offset:3072
	global_load_dwordx4 v[164:167], v[26:27], off
	global_load_dwordx4 v[190:193], v[2:3], off
	global_load_dwordx4 v[4:7], v[14:15], off
	global_load_dwordx4 v[168:171], v[26:27], off offset:1024
	global_load_dwordx4 v[198:201], v[2:3], off offset:1024
	global_load_dwordx4 v[8:11], v[14:15], off offset:1024
	global_load_dwordx4 v[172:175], v[26:27], off offset:2048
	global_load_dwordx4 v[202:205], v[2:3], off offset:2048
	global_load_dwordx4 v[20:23], v[14:15], off offset:2048
	global_load_dwordx4 v[186:189], v[26:27], off offset:3072
	global_load_dwordx4 v[206:209], v[2:3], off offset:3072
	global_load_dwordx4 v[30:33], v[14:15], off offset:3072
	v_add_u32_e32 v54, s9, v54
	s_waitcnt vmcnt(12)
	v_mul_f32_e32 v56, v148, v148
	v_mul_f32_e32 v57, v149, v149
	v_fmac_f32_e32 v56, v150, v150
	v_fmac_f32_e32 v57, v151, v151
	v_fmac_f32_e32 v56, v152, v152
	v_fmac_f32_e32 v57, v153, v153
	v_fmac_f32_e32 v56, v154, v154
	v_fmac_f32_e32 v57, v155, v155
	v_fmac_f32_e32 v56, v156, v156
	v_fmac_f32_e32 v57, v157, v157
	v_fmac_f32_e32 v56, v158, v158
	v_fmac_f32_e32 v57, v159, v159
	v_fmac_f32_e32 v56, v160, v160
	v_fmac_f32_e32 v57, v161, v161
	v_fmac_f32_e32 v56, v162, v162
	v_fmac_f32_e32 v57, v163, v163
	v_add_f32_e32 v56, v56, v57
	s_nop 1
	v_add_f32_dpp v56, v56, v56 quad_perm:[1,0,3,2] row_mask:0xf bank_mask:0xf
	s_nop 1
	v_add_f32_dpp v56, v56, v56 quad_perm:[2,3,0,1] row_mask:0xf bank_mask:0xf
	s_nop 1
	v_add_f32_dpp v56, v56, v56 row_half_mirror row_mask:0xf bank_mask:0xf
	s_nop 1
	v_add_f32_dpp v56, v56, v56 row_mirror row_mask:0xf bank_mask:0xf
	v_mov_b32_e32 v57, v56
	s_nop 1
	v_permlane16_swap_b32_e32 v56, v57
	v_add_f32_e32 v56, v56, v57
	v_mov_b32_e32 v57, v56
	s_nop 1
	v_permlane32_swap_b32_e32 v56, v57
	v_add_f32_e32 v56, v56, v57
	v_fmamk_f32 v56, v56, 0x3a800000, v210
	v_cmp_gt_f32_e32 vcc, s11, v56
	v_mul_f32_e32 v57, 0x4b800000, v56
	s_nop 0
	v_cndmask_b32_e32 v56, v56, v57, vcc
	v_rsq_f32_e32 v56, v56
	s_nop 0
	v_mul_f32_e32 v57, 0x45800000, v56
	v_cndmask_b32_e32 v58, v56, v57, vcc
	s_waitcnt vmcnt(0)
	v_mul_f32_e32 v148, v148, v58
	v_add_f32_e32 v4, 1.0, v4
	v_mul_f32_e32 v148, v164, v148
	v_fma_f32 v148, v148, v4, v190
	v_mul_f32_e32 v149, v149, v58
	v_add_f32_e32 v5, 1.0, v5
	v_mul_f32_e32 v149, v165, v149
	v_fma_f32 v149, v149, v5, v191
	v_mul_f32_e32 v150, v150, v58
	v_add_f32_e32 v6, 1.0, v6
	v_mul_f32_e32 v150, v166, v150
	v_fma_f32 v150, v150, v6, v192
	v_mul_f32_e32 v151, v151, v58
	v_add_f32_e32 v7, 1.0, v7
	v_mul_f32_e32 v151, v167, v151
	v_fma_f32 v151, v151, v7, v193
	v_cvt_pk_bf16_f32 v148, v148, v149
	v_cvt_pk_bf16_f32 v149, v150, v151
	global_store_dwordx2 v[36:37], v[148:149], off
	v_mul_f32_e32 v152, v152, v58
	v_add_f32_e32 v8, 1.0, v8
	v_mul_f32_e32 v152, v168, v152
	v_fma_f32 v152, v152, v8, v198
	v_mul_f32_e32 v153, v153, v58
	v_add_f32_e32 v9, 1.0, v9
	v_mul_f32_e32 v153, v169, v153
	v_fma_f32 v153, v153, v9, v199
	v_mul_f32_e32 v154, v154, v58
	v_add_f32_e32 v10, 1.0, v10
	v_mul_f32_e32 v154, v170, v154
	v_fma_f32 v154, v154, v10, v200
	v_mul_f32_e32 v155, v155, v58
	v_add_f32_e32 v11, 1.0, v11
	v_mul_f32_e32 v155, v171, v155
	v_fma_f32 v155, v155, v11, v201
	v_cvt_pk_bf16_f32 v152, v152, v153
	v_cvt_pk_bf16_f32 v153, v154, v155
	global_store_dwordx2 v[36:37], v[152:153], off offset:512
	v_mul_f32_e32 v156, v156, v58
	v_add_f32_e32 v20, 1.0, v20
	v_mul_f32_e32 v156, v172, v156
	v_fma_f32 v156, v156, v20, v202
	v_mul_f32_e32 v157, v157, v58
	v_add_f32_e32 v21, 1.0, v21
	v_mul_f32_e32 v157, v173, v157
	v_fma_f32 v157, v157, v21, v203
	v_mul_f32_e32 v158, v158, v58
	v_add_f32_e32 v22, 1.0, v22
	v_mul_f32_e32 v158, v174, v158
	v_fma_f32 v158, v158, v22, v204
	v_mul_f32_e32 v159, v159, v58
	v_add_f32_e32 v23, 1.0, v23
	v_mul_f32_e32 v159, v175, v159
	v_fma_f32 v159, v159, v23, v205
	v_cvt_pk_bf16_f32 v156, v156, v157
	v_cvt_pk_bf16_f32 v157, v158, v159
	global_store_dwordx2 v[36:37], v[156:157], off offset:1024
	v_mul_f32_e32 v160, v160, v58
	v_add_f32_e32 v30, 1.0, v30
	v_mul_f32_e32 v160, v186, v160
	v_fma_f32 v160, v160, v30, v206
	v_mul_f32_e32 v161, v161, v58
	v_add_f32_e32 v31, 1.0, v31
	v_mul_f32_e32 v161, v187, v161
	v_fma_f32 v161, v161, v31, v207
	v_mul_f32_e32 v162, v162, v58
	v_add_f32_e32 v32, 1.0, v32
	v_mul_f32_e32 v162, v188, v162
	v_fma_f32 v162, v162, v32, v208
	v_mul_f32_e32 v163, v163, v58
	v_add_f32_e32 v33, 1.0, v33
	v_mul_f32_e32 v163, v189, v163
	v_fma_f32 v163, v163, v33, v209
	v_cvt_pk_bf16_f32 v160, v160, v161
	v_cvt_pk_bf16_f32 v161, v162, v163
	global_store_dwordx2 v[36:37], v[160:161], off offset:1536
	v_add_u32_e32 v2, 0x4000, v54
	v_cmp_lt_i32_e32 vcc, s14, v2
	s_or_b64 s[2:3], vcc, s[2:3]
	s_andn2_b64 exec, exec, s[2:3]
	s_cbranch_execnz .LBB0_223
